# GDN prompt scan: exact counted vmcnt for the 10-stage operand ring (38..54 instead of hipcc's 16..22), so old snapshot stores no longer gate each step
# speedup vs baseline: 1.0016x; 1.0016x over previous
.LBB0_908:
	v_lshl_add_u64 v[190:191], v[188:189], 0, s[6:7]
	v_cvt_pk_bf16_f32 v164, v164, v165
	v_cvt_pk_bf16_f32 v165, v166, v167
	v_cvt_pk_bf16_f32 v167, v170, v171
	v_cvt_pk_bf16_f32 v170, v160, v161
	v_add_co_u32_e32 v160, vcc, s11, v190
	v_cvt_pk_bf16_f32 v166, v168, v169
	v_cvt_pk_bf16_f32 v168, v172, v173
	v_cvt_pk_bf16_f32 v169, v174, v175
	v_cvt_pk_bf16_f32 v171, v162, v163
	v_addc_co_u32_e32 v161, vcc, 0, v191, vcc
	ds_write_b64 v193, v[164:165]
	ds_write_b64 v193, v[166:167] offset:2304
	ds_write_b64 v193, v[168:169] offset:4608
	ds_write_b64 v194, v[170:171]
	s_nop 1
	v_permlane32_swap_b32_e32 v164, v168
	v_permlane32_swap_b32_e32 v165, v169
	v_permlane32_swap_b32_e32 v166, v170
	v_permlane32_swap_b32_e32 v167, v171
	global_store_dwordx4 v[160:161], v[164:167], off
	global_store_dwordx4 v[160:161], v[168:171], off offset:1024
	s_waitcnt lgkmcnt(0)
	s_barrier
	ds_read_b128 v[164:167], v195
	ds_read_b128 v[168:171], v195 offset:64
	s_waitcnt vmcnt(38)
	v_lshlrev_b32_e32 v160, 16, v12
	v_and_b32_e32 v161, 0xffff0000, v12
	v_lshlrev_b32_e32 v162, 16, v13
	v_and_b32_e32 v163, 0xffff0000, v13
	ds_read_b128 v[172:175], v195 offset:2368
	ds_read_b128 v[198:201], v195 offset:4672
	s_waitcnt lgkmcnt(3)
	v_mfma_f32_16x16x32_bf16 v[160:163], v[0:3], v[164:167], v[160:163]
	v_lshlrev_b32_e32 v164, 16, v14
	v_and_b32_e32 v165, 0xffff0000, v14
	v_lshlrev_b32_e32 v166, 16, v15
	s_waitcnt lgkmcnt(2)
	v_mfma_f32_16x16x32_bf16 v[160:163], v[4:7], v[168:171], v[160:163]
	ds_read_b128 v[168:171], v195 offset:2304
	v_and_b32_e32 v167, 0xffff0000, v15
	ds_read_b128 v[202:205], v196 offset:64
	s_cmpk_lt_u32 s34, 0x76
	s_waitcnt lgkmcnt(1)
	v_mfma_f32_16x16x32_bf16 v[164:167], v[0:3], v[168:171], v[164:167]
	v_lshlrev_b32_e32 v168, 16, v8
	v_and_b32_e32 v169, 0xffff0000, v8
	v_lshlrev_b32_e32 v170, 16, v9
	v_mfma_f32_16x16x32_bf16 v[164:167], v[4:7], v[172:175], v[164:167]
	ds_read_b128 v[172:175], v195 offset:4608
	v_and_b32_e32 v171, 0xffff0000, v9
	s_cselect_b64 s[8:9], -1, 0
	s_and_b64 vcc, exec, s[8:9]
	s_waitcnt lgkmcnt(0)
	v_mfma_f32_16x16x32_bf16 v[168:171], v[0:3], v[172:175], v[168:171]
	v_lshlrev_b32_e32 v172, 16, v10
	v_and_b32_e32 v173, 0xffff0000, v10
	v_lshlrev_b32_e32 v174, 16, v11
	v_mfma_f32_16x16x32_bf16 v[168:171], v[4:7], v[198:201], v[168:171]
	ds_read_b128 v[198:201], v196
	v_and_b32_e32 v175, 0xffff0000, v11
	s_waitcnt lgkmcnt(0)
	s_nop 0
	v_mfma_f32_16x16x32_bf16 v[172:175], v[0:3], v[198:201], v[172:175]
	v_mfma_f32_16x16x32_bf16 v[172:175], v[4:7], v[202:205], v[172:175]
	s_cbranch_vccz .LBB0_910
	s_add_i32 s0, s4, 0xffff7000
	s_lshl_b64 s[24:25], s[0:1], 1
	v_lshl_add_u64 v[4:5], v[176:177], 0, s[24:25]
	v_lshl_add_u64 v[12:13], v[178:179], 0, s[24:25]
	global_load_dwordx4 v[0:3], v[4:5], off
	s_nop 0
	global_load_dwordx4 v[4:7], v[4:5], off offset:64
	s_nop 0
	global_load_dwordx4 v[8:11], v[12:13], off offset:16
	s_nop 0
	global_load_dwordx4 v[12:15], v[12:13], off
.LBB0_910:
	v_cvt_pk_bf16_f32 v160, v160, v161
	v_cvt_pk_bf16_f32 v161, v162, v163
	v_cvt_pk_bf16_f32 v162, v164, v165
	v_cvt_pk_bf16_f32 v164, v168, v169
	v_add_co_u32_e32 v168, vcc, s12, v190
	v_cvt_pk_bf16_f32 v163, v166, v167
	v_cvt_pk_bf16_f32 v165, v170, v171
	v_cvt_pk_bf16_f32 v166, v172, v173
	v_cvt_pk_bf16_f32 v167, v174, v175
	v_addc_co_u32_e32 v169, vcc, 0, v191, vcc
	ds_write_b64 v193, v[160:161] offset:9216
	ds_write_b64 v193, v[162:163] offset:11520
	ds_write_b64 v193, v[164:165] offset:13824
	ds_write_b64 v194, v[166:167] offset:9216
	s_nop 1
	v_permlane32_swap_b32_e32 v160, v164
	v_permlane32_swap_b32_e32 v161, v165
	v_permlane32_swap_b32_e32 v162, v166
	v_permlane32_swap_b32_e32 v163, v167
	global_store_dwordx4 v[168:169], v[160:163], off
	global_store_dwordx4 v[168:169], v[164:167], off offset:1024
	s_waitcnt lgkmcnt(0)
	s_barrier
	ds_read_b128 v[164:167], v195 offset:9216
	ds_read_b128 v[168:171], v195 offset:9280
	s_waitcnt vmcnt(40)
	v_lshlrev_b32_e32 v160, 16, v28
	v_and_b32_e32 v161, 0xffff0000, v28
	v_lshlrev_b32_e32 v162, 16, v29
	v_and_b32_e32 v163, 0xffff0000, v29
	ds_read_b128 v[172:175], v195 offset:11584
	ds_read_b128 v[198:201], v195 offset:13888
	s_waitcnt lgkmcnt(3)
	v_mfma_f32_16x16x32_bf16 v[160:163], v[16:19], v[164:167], v[160:163]
	v_lshlrev_b32_e32 v164, 16, v30
	v_and_b32_e32 v165, 0xffff0000, v30
	v_lshlrev_b32_e32 v166, 16, v31
	s_waitcnt lgkmcnt(2)
	v_mfma_f32_16x16x32_bf16 v[160:163], v[20:23], v[168:171], v[160:163]
	ds_read_b128 v[168:171], v195 offset:11520
	v_and_b32_e32 v167, 0xffff0000, v31
	ds_read_b128 v[202:205], v196 offset:9280
	s_andn2_b64 vcc, exec, s[8:9]
	s_waitcnt lgkmcnt(1)
	v_mfma_f32_16x16x32_bf16 v[164:167], v[16:19], v[168:171], v[164:167]
	v_lshlrev_b32_e32 v168, 16, v24
	v_and_b32_e32 v169, 0xffff0000, v24
	v_lshlrev_b32_e32 v170, 16, v25
	v_mfma_f32_16x16x32_bf16 v[164:167], v[20:23], v[172:175], v[164:167]
	ds_read_b128 v[172:175], v195 offset:13824
	v_and_b32_e32 v171, 0xffff0000, v25
	s_waitcnt lgkmcnt(0)
	s_nop 0
	v_mfma_f32_16x16x32_bf16 v[168:171], v[16:19], v[172:175], v[168:171]
	v_lshlrev_b32_e32 v172, 16, v26
	v_and_b32_e32 v173, 0xffff0000, v26
	v_lshlrev_b32_e32 v174, 16, v27
	v_mfma_f32_16x16x32_bf16 v[168:171], v[20:23], v[198:201], v[168:171]
	ds_read_b128 v[198:201], v196 offset:9216
	v_and_b32_e32 v175, 0xffff0000, v27
	s_waitcnt lgkmcnt(0)
	s_nop 0
	v_mfma_f32_16x16x32_bf16 v[172:175], v[16:19], v[198:201], v[172:175]
	v_mfma_f32_16x16x32_bf16 v[172:175], v[20:23], v[202:205], v[172:175]
	s_cbranch_vccnz .LBB0_912
	s_add_i32 s0, s4, 0xffff8000
	s_lshl_b64 s[8:9], s[0:1], 1
	v_lshl_add_u64 v[20:21], v[176:177], 0, s[8:9]
	v_lshl_add_u64 v[28:29], v[178:179], 0, s[8:9]
	global_load_dwordx4 v[16:19], v[20:21], off
	s_nop 0
	global_load_dwordx4 v[20:23], v[20:21], off offset:64
	s_nop 0
	global_load_dwordx4 v[24:27], v[28:29], off offset:16
	s_nop 0
	global_load_dwordx4 v[28:31], v[28:29], off
.LBB0_912:
	v_cvt_pk_bf16_f32 v160, v160, v161
	v_cvt_pk_bf16_f32 v161, v162, v163
	v_cvt_pk_bf16_f32 v162, v164, v165
	v_cvt_pk_bf16_f32 v164, v168, v169
	v_add_co_u32_e32 v168, vcc, s13, v190
	v_cvt_pk_bf16_f32 v163, v166, v167
	v_cvt_pk_bf16_f32 v165, v170, v171
	v_cvt_pk_bf16_f32 v166, v172, v173
	v_cvt_pk_bf16_f32 v167, v174, v175
	v_addc_co_u32_e32 v169, vcc, 0, v191, vcc
	ds_write_b64 v193, v[160:161]
	ds_write_b64 v193, v[162:163] offset:2304
	ds_write_b64 v193, v[164:165] offset:4608
	ds_write_b64 v194, v[166:167]
	s_nop 1
	v_permlane32_swap_b32_e32 v160, v164
	v_permlane32_swap_b32_e32 v161, v165
	v_permlane32_swap_b32_e32 v162, v166
	v_permlane32_swap_b32_e32 v163, v167
	global_store_dwordx4 v[168:169], v[160:163], off
	global_store_dwordx4 v[168:169], v[164:167], off offset:1024
	s_waitcnt lgkmcnt(0)
	s_barrier
	ds_read_b128 v[164:167], v195
	ds_read_b128 v[168:171], v195 offset:64
	s_waitcnt vmcnt(40)
	v_lshlrev_b32_e32 v160, 16, v44
	v_and_b32_e32 v161, 0xffff0000, v44
	v_lshlrev_b32_e32 v162, 16, v45
	v_and_b32_e32 v163, 0xffff0000, v45
	ds_read_b128 v[172:175], v195 offset:2368
	ds_read_b128 v[198:201], v195 offset:4672
	s_waitcnt lgkmcnt(3)
	v_mfma_f32_16x16x32_bf16 v[160:163], v[32:35], v[164:167], v[160:163]
	v_lshlrev_b32_e32 v164, 16, v46
	v_and_b32_e32 v165, 0xffff0000, v46
	v_lshlrev_b32_e32 v166, 16, v47
	s_waitcnt lgkmcnt(2)
	v_mfma_f32_16x16x32_bf16 v[160:163], v[36:39], v[168:171], v[160:163]
	ds_read_b128 v[168:171], v195 offset:2304
	v_and_b32_e32 v167, 0xffff0000, v47
	ds_read_b128 v[202:205], v196 offset:64
	s_cmpk_gt_u32 s34, 0x73
	s_waitcnt lgkmcnt(1)
	v_mfma_f32_16x16x32_bf16 v[164:167], v[32:35], v[168:171], v[164:167]
	v_lshlrev_b32_e32 v168, 16, v40
	v_and_b32_e32 v169, 0xffff0000, v40
	v_lshlrev_b32_e32 v170, 16, v41
	v_mfma_f32_16x16x32_bf16 v[164:167], v[36:39], v[172:175], v[164:167]
	ds_read_b128 v[172:175], v195 offset:4608
	v_and_b32_e32 v171, 0xffff0000, v41
	s_waitcnt lgkmcnt(0)
	s_nop 0
	v_mfma_f32_16x16x32_bf16 v[168:171], v[32:35], v[172:175], v[168:171]
	v_lshlrev_b32_e32 v172, 16, v42
	v_and_b32_e32 v173, 0xffff0000, v42
	v_lshlrev_b32_e32 v174, 16, v43
	v_mfma_f32_16x16x32_bf16 v[168:171], v[36:39], v[198:201], v[168:171]
	ds_read_b128 v[198:201], v196
	v_and_b32_e32 v175, 0xffff0000, v43
	s_waitcnt lgkmcnt(0)
	s_nop 0
	v_mfma_f32_16x16x32_bf16 v[172:175], v[32:35], v[198:201], v[172:175]
	v_mfma_f32_16x16x32_bf16 v[172:175], v[36:39], v[202:205], v[172:175]
	s_cbranch_scc1 .LBB0_914
	s_add_i32 s0, s4, 0xffff9000
	s_lshl_b64 s[8:9], s[0:1], 1
	v_lshl_add_u64 v[36:37], v[176:177], 0, s[8:9]
	v_lshl_add_u64 v[44:45], v[178:179], 0, s[8:9]
	global_load_dwordx4 v[32:35], v[36:37], off
	s_nop 0
	global_load_dwordx4 v[36:39], v[36:37], off offset:64
	s_nop 0
	global_load_dwordx4 v[40:43], v[44:45], off offset:16
	s_nop 0
	global_load_dwordx4 v[44:47], v[44:45], off
.LBB0_914:
	v_cvt_pk_bf16_f32 v160, v160, v161
	v_cvt_pk_bf16_f32 v161, v162, v163
	v_cvt_pk_bf16_f32 v162, v164, v165
	v_cvt_pk_bf16_f32 v164, v168, v169
	v_add_co_u32_e32 v168, vcc, s14, v190
	v_cvt_pk_bf16_f32 v163, v166, v167
	v_cvt_pk_bf16_f32 v165, v170, v171
	v_cvt_pk_bf16_f32 v166, v172, v173
	v_cvt_pk_bf16_f32 v167, v174, v175
	v_addc_co_u32_e32 v169, vcc, 0, v191, vcc
	ds_write_b64 v193, v[160:161] offset:9216
	ds_write_b64 v193, v[162:163] offset:11520
	ds_write_b64 v193, v[164:165] offset:13824
	ds_write_b64 v194, v[166:167] offset:9216
	s_nop 1
	v_permlane32_swap_b32_e32 v160, v164
	v_permlane32_swap_b32_e32 v161, v165
	v_permlane32_swap_b32_e32 v162, v166
	v_permlane32_swap_b32_e32 v163, v167
	global_store_dwordx4 v[168:169], v[160:163], off
	global_store_dwordx4 v[168:169], v[164:167], off offset:1024
	s_waitcnt lgkmcnt(0)
	s_barrier
	ds_read_b128 v[164:167], v195 offset:9216
	ds_read_b128 v[168:171], v195 offset:9280
	s_waitcnt vmcnt(36)
	v_lshlrev_b32_e32 v160, 16, v60
	v_and_b32_e32 v161, 0xffff0000, v60
	v_lshlrev_b32_e32 v162, 16, v61
	v_and_b32_e32 v163, 0xffff0000, v61
	ds_read_b128 v[172:175], v195 offset:11584
	ds_read_b128 v[198:201], v195 offset:13888
	s_waitcnt lgkmcnt(3)
	v_mfma_f32_16x16x32_bf16 v[160:163], v[48:51], v[164:167], v[160:163]
	v_lshlrev_b32_e32 v164, 16, v62
	v_and_b32_e32 v165, 0xffff0000, v62
	v_lshlrev_b32_e32 v166, 16, v63
	s_waitcnt lgkmcnt(2)
	v_mfma_f32_16x16x32_bf16 v[160:163], v[52:55], v[168:171], v[160:163]
	ds_read_b128 v[168:171], v195 offset:11520
	v_and_b32_e32 v167, 0xffff0000, v63
	ds_read_b128 v[202:205], v196 offset:9280
	s_cmpk_gt_u32 s34, 0x72
	s_waitcnt lgkmcnt(1)
	v_mfma_f32_16x16x32_bf16 v[164:167], v[48:51], v[168:171], v[164:167]
	v_lshlrev_b32_e32 v168, 16, v56
	v_and_b32_e32 v169, 0xffff0000, v56
	v_lshlrev_b32_e32 v170, 16, v57
	v_mfma_f32_16x16x32_bf16 v[164:167], v[52:55], v[172:175], v[164:167]
	ds_read_b128 v[172:175], v195 offset:13824
	v_and_b32_e32 v171, 0xffff0000, v57
	s_waitcnt lgkmcnt(0)
	s_nop 0
	v_mfma_f32_16x16x32_bf16 v[168:171], v[48:51], v[172:175], v[168:171]
	v_lshlrev_b32_e32 v172, 16, v58
	v_and_b32_e32 v173, 0xffff0000, v58
	v_lshlrev_b32_e32 v174, 16, v59
	v_mfma_f32_16x16x32_bf16 v[168:171], v[52:55], v[198:201], v[168:171]
	ds_read_b128 v[198:201], v196 offset:9216
	v_and_b32_e32 v175, 0xffff0000, v59
	s_waitcnt lgkmcnt(0)
	s_nop 0
	v_mfma_f32_16x16x32_bf16 v[172:175], v[48:51], v[198:201], v[172:175]
	v_mfma_f32_16x16x32_bf16 v[172:175], v[52:55], v[202:205], v[172:175]
	s_cbranch_scc1 .LBB0_916
	s_add_i32 s0, s4, 0xffffa000
	s_lshl_b64 s[8:9], s[0:1], 1
	v_lshl_add_u64 v[52:53], v[176:177], 0, s[8:9]
	v_lshl_add_u64 v[60:61], v[178:179], 0, s[8:9]
	global_load_dwordx4 v[48:51], v[52:53], off
	s_nop 0
	global_load_dwordx4 v[52:55], v[52:53], off offset:64
	s_nop 0
	global_load_dwordx4 v[56:59], v[60:61], off offset:16
	s_nop 0
	global_load_dwordx4 v[60:63], v[60:61], off
.LBB0_916:
	v_cvt_pk_bf16_f32 v160, v160, v161
	v_cvt_pk_bf16_f32 v161, v162, v163
	v_cvt_pk_bf16_f32 v162, v164, v165
	v_cvt_pk_bf16_f32 v164, v168, v169
	v_add_co_u32_e32 v168, vcc, s15, v190
	v_cvt_pk_bf16_f32 v163, v166, v167
	v_cvt_pk_bf16_f32 v165, v170, v171
	v_cvt_pk_bf16_f32 v166, v172, v173
	v_cvt_pk_bf16_f32 v167, v174, v175
	v_addc_co_u32_e32 v169, vcc, 0, v191, vcc
	ds_write_b64 v193, v[160:161]
	ds_write_b64 v193, v[162:163] offset:2304
	ds_write_b64 v193, v[164:165] offset:4608
	ds_write_b64 v194, v[166:167]
	s_nop 1
	v_permlane32_swap_b32_e32 v160, v164
	v_permlane32_swap_b32_e32 v161, v165
	v_permlane32_swap_b32_e32 v162, v166
	v_permlane32_swap_b32_e32 v163, v167
	global_store_dwordx4 v[168:169], v[160:163], off
	global_store_dwordx4 v[168:169], v[164:167], off offset:1024
	s_waitcnt lgkmcnt(0)
	s_barrier
	ds_read_b128 v[164:167], v195
	ds_read_b128 v[168:171], v195 offset:64
	s_waitcnt vmcnt(32)
	v_lshlrev_b32_e32 v160, 16, v76
	v_and_b32_e32 v161, 0xffff0000, v76
	v_lshlrev_b32_e32 v162, 16, v77
	v_and_b32_e32 v163, 0xffff0000, v77
	ds_read_b128 v[172:175], v195 offset:2368
	ds_read_b128 v[198:201], v195 offset:4672
	s_waitcnt lgkmcnt(3)
	v_mfma_f32_16x16x32_bf16 v[160:163], v[64:67], v[164:167], v[160:163]
	v_lshlrev_b32_e32 v164, 16, v78
	v_and_b32_e32 v165, 0xffff0000, v78
	v_lshlrev_b32_e32 v166, 16, v79
	s_waitcnt lgkmcnt(2)
	v_mfma_f32_16x16x32_bf16 v[160:163], v[68:71], v[168:171], v[160:163]
	ds_read_b128 v[168:171], v195 offset:2304
	v_and_b32_e32 v167, 0xffff0000, v79
	ds_read_b128 v[202:205], v196 offset:64
	s_cmpk_gt_u32 s34, 0x71
	s_waitcnt lgkmcnt(1)
	v_mfma_f32_16x16x32_bf16 v[164:167], v[64:67], v[168:171], v[164:167]
	v_lshlrev_b32_e32 v168, 16, v72
	v_and_b32_e32 v169, 0xffff0000, v72
	v_lshlrev_b32_e32 v170, 16, v73
	v_mfma_f32_16x16x32_bf16 v[164:167], v[68:71], v[172:175], v[164:167]
	ds_read_b128 v[172:175], v195 offset:4608
	v_and_b32_e32 v171, 0xffff0000, v73
	s_waitcnt lgkmcnt(0)
	s_nop 0
	v_mfma_f32_16x16x32_bf16 v[168:171], v[64:67], v[172:175], v[168:171]
	v_lshlrev_b32_e32 v172, 16, v74
	v_and_b32_e32 v173, 0xffff0000, v74
	v_lshlrev_b32_e32 v174, 16, v75
	v_mfma_f32_16x16x32_bf16 v[168:171], v[68:71], v[198:201], v[168:171]
	ds_read_b128 v[198:201], v196
	v_and_b32_e32 v175, 0xffff0000, v75
	s_waitcnt lgkmcnt(0)
	s_nop 0
	v_mfma_f32_16x16x32_bf16 v[172:175], v[64:67], v[198:201], v[172:175]
	v_mfma_f32_16x16x32_bf16 v[172:175], v[68:71], v[202:205], v[172:175]
	s_cbranch_scc1 .LBB0_918
	s_add_i32 s0, s4, 0xffffb000
	s_lshl_b64 s[8:9], s[0:1], 1
	v_lshl_add_u64 v[68:69], v[176:177], 0, s[8:9]
	v_lshl_add_u64 v[76:77], v[178:179], 0, s[8:9]
	global_load_dwordx4 v[64:67], v[68:69], off
	s_nop 0
	global_load_dwordx4 v[68:71], v[68:69], off offset:64
	s_nop 0
	global_load_dwordx4 v[72:75], v[76:77], off offset:16
	s_nop 0
	global_load_dwordx4 v[76:79], v[76:77], off
.LBB0_918:
	v_cvt_pk_bf16_f32 v160, v160, v161
	v_cvt_pk_bf16_f32 v161, v162, v163
	v_cvt_pk_bf16_f32 v162, v164, v165
	v_cvt_pk_bf16_f32 v164, v168, v169
	v_add_co_u32_e32 v168, vcc, s16, v190
	v_cvt_pk_bf16_f32 v163, v166, v167
	v_cvt_pk_bf16_f32 v165, v170, v171
	v_cvt_pk_bf16_f32 v166, v172, v173
	v_cvt_pk_bf16_f32 v167, v174, v175
	v_addc_co_u32_e32 v169, vcc, 0, v191, vcc
	ds_write_b64 v193, v[160:161] offset:9216
	ds_write_b64 v193, v[162:163] offset:11520
	ds_write_b64 v193, v[164:165] offset:13824
	ds_write_b64 v194, v[166:167] offset:9216
	s_nop 1
	v_permlane32_swap_b32_e32 v160, v164
	v_permlane32_swap_b32_e32 v161, v165
	v_permlane32_swap_b32_e32 v162, v166
	v_permlane32_swap_b32_e32 v163, v167
	global_store_dwordx4 v[168:169], v[160:163], off
	global_store_dwordx4 v[168:169], v[164:167], off offset:1024
	s_waitcnt lgkmcnt(0)
	s_barrier
	ds_read_b128 v[164:167], v195 offset:9216
	ds_read_b128 v[168:171], v195 offset:9280
	s_waitcnt vmcnt(28)
	v_lshlrev_b32_e32 v160, 16, v92
	v_and_b32_e32 v161, 0xffff0000, v92
	v_lshlrev_b32_e32 v162, 16, v93
	v_and_b32_e32 v163, 0xffff0000, v93
	ds_read_b128 v[172:175], v195 offset:11584
	ds_read_b128 v[198:201], v195 offset:13888
	s_waitcnt lgkmcnt(3)
	v_mfma_f32_16x16x32_bf16 v[160:163], v[80:83], v[164:167], v[160:163]
	v_lshlrev_b32_e32 v164, 16, v94
	v_and_b32_e32 v165, 0xffff0000, v94
	v_lshlrev_b32_e32 v166, 16, v95
	s_waitcnt lgkmcnt(2)
	v_mfma_f32_16x16x32_bf16 v[160:163], v[84:87], v[168:171], v[160:163]
	ds_read_b128 v[168:171], v195 offset:11520
	v_and_b32_e32 v167, 0xffff0000, v95
	ds_read_b128 v[202:205], v196 offset:9280
	s_cmpk_gt_u32 s34, 0x70
	s_waitcnt lgkmcnt(1)
	v_mfma_f32_16x16x32_bf16 v[164:167], v[80:83], v[168:171], v[164:167]
	v_lshlrev_b32_e32 v168, 16, v88
	v_and_b32_e32 v169, 0xffff0000, v88
	v_lshlrev_b32_e32 v170, 16, v89
	v_mfma_f32_16x16x32_bf16 v[164:167], v[84:87], v[172:175], v[164:167]
	ds_read_b128 v[172:175], v195 offset:13824
	v_and_b32_e32 v171, 0xffff0000, v89
	s_waitcnt lgkmcnt(0)
	s_nop 0
	v_mfma_f32_16x16x32_bf16 v[168:171], v[80:83], v[172:175], v[168:171]
	v_lshlrev_b32_e32 v172, 16, v90
	v_and_b32_e32 v173, 0xffff0000, v90
	v_lshlrev_b32_e32 v174, 16, v91
	v_mfma_f32_16x16x32_bf16 v[168:171], v[84:87], v[198:201], v[168:171]
	ds_read_b128 v[198:201], v196 offset:9216
	v_and_b32_e32 v175, 0xffff0000, v91
	s_waitcnt lgkmcnt(0)
	s_nop 0
	v_mfma_f32_16x16x32_bf16 v[172:175], v[80:83], v[198:201], v[172:175]
	v_mfma_f32_16x16x32_bf16 v[172:175], v[84:87], v[202:205], v[172:175]
	s_cbranch_scc1 .LBB0_920
	s_add_i32 s0, s4, 0xffffc000
	s_lshl_b64 s[8:9], s[0:1], 1
	v_lshl_add_u64 v[84:85], v[176:177], 0, s[8:9]
	v_lshl_add_u64 v[92:93], v[178:179], 0, s[8:9]
	global_load_dwordx4 v[80:83], v[84:85], off
	s_nop 0
	global_load_dwordx4 v[84:87], v[84:85], off offset:64
	s_nop 0
	global_load_dwordx4 v[88:91], v[92:93], off offset:16
	s_nop 0
	global_load_dwordx4 v[92:95], v[92:93], off
.LBB0_920:
	v_cvt_pk_bf16_f32 v160, v160, v161
	v_cvt_pk_bf16_f32 v161, v162, v163
	v_cvt_pk_bf16_f32 v162, v164, v165
	v_cvt_pk_bf16_f32 v164, v168, v169
	v_add_co_u32_e32 v168, vcc, s17, v190
	v_cvt_pk_bf16_f32 v163, v166, v167
	v_cvt_pk_bf16_f32 v165, v170, v171
	v_cvt_pk_bf16_f32 v166, v172, v173
	v_cvt_pk_bf16_f32 v167, v174, v175
	v_addc_co_u32_e32 v169, vcc, 0, v191, vcc
	ds_write_b64 v193, v[160:161]
	ds_write_b64 v193, v[162:163] offset:2304
	ds_write_b64 v193, v[164:165] offset:4608
	ds_write_b64 v194, v[166:167]
	s_nop 1
	v_permlane32_swap_b32_e32 v160, v164
	v_permlane32_swap_b32_e32 v161, v165
	v_permlane32_swap_b32_e32 v162, v166
	v_permlane32_swap_b32_e32 v163, v167
	global_store_dwordx4 v[168:169], v[160:163], off
	global_store_dwordx4 v[168:169], v[164:167], off offset:1024
	s_waitcnt lgkmcnt(0)
	s_barrier
	ds_read_b128 v[164:167], v195
	ds_read_b128 v[168:171], v195 offset:64
	s_waitcnt vmcnt(24)
	v_lshlrev_b32_e32 v160, 16, v108
	v_and_b32_e32 v161, 0xffff0000, v108
	v_lshlrev_b32_e32 v162, 16, v109
	v_and_b32_e32 v163, 0xffff0000, v109
	ds_read_b128 v[172:175], v195 offset:2368
	ds_read_b128 v[198:201], v195 offset:4672
	s_waitcnt lgkmcnt(3)
	v_mfma_f32_16x16x32_bf16 v[160:163], v[96:99], v[164:167], v[160:163]
	v_lshlrev_b32_e32 v164, 16, v110
	v_and_b32_e32 v165, 0xffff0000, v110
	v_lshlrev_b32_e32 v166, 16, v111
	s_waitcnt lgkmcnt(2)
	v_mfma_f32_16x16x32_bf16 v[160:163], v[100:103], v[168:171], v[160:163]
	ds_read_b128 v[168:171], v195 offset:2304
	v_and_b32_e32 v167, 0xffff0000, v111
	ds_read_b128 v[202:205], v196 offset:64
	s_cmpk_gt_u32 s34, 0x6f
	s_waitcnt lgkmcnt(1)
	v_mfma_f32_16x16x32_bf16 v[164:167], v[96:99], v[168:171], v[164:167]
	v_lshlrev_b32_e32 v168, 16, v104
	v_and_b32_e32 v169, 0xffff0000, v104
	v_lshlrev_b32_e32 v170, 16, v105
	v_mfma_f32_16x16x32_bf16 v[164:167], v[100:103], v[172:175], v[164:167]
	ds_read_b128 v[172:175], v195 offset:4608
	v_and_b32_e32 v171, 0xffff0000, v105
	s_waitcnt lgkmcnt(0)
	s_nop 0
	v_mfma_f32_16x16x32_bf16 v[168:171], v[96:99], v[172:175], v[168:171]
	v_lshlrev_b32_e32 v172, 16, v106
	v_and_b32_e32 v173, 0xffff0000, v106
	v_lshlrev_b32_e32 v174, 16, v107
	v_mfma_f32_16x16x32_bf16 v[168:171], v[100:103], v[198:201], v[168:171]
	ds_read_b128 v[198:201], v196
	v_and_b32_e32 v175, 0xffff0000, v107
	s_waitcnt lgkmcnt(0)
	s_nop 0
	v_mfma_f32_16x16x32_bf16 v[172:175], v[96:99], v[198:201], v[172:175]
	v_mfma_f32_16x16x32_bf16 v[172:175], v[100:103], v[202:205], v[172:175]
	s_cbranch_scc1 .LBB0_922
	s_add_i32 s0, s4, 0xffffd000
	s_lshl_b64 s[8:9], s[0:1], 1
	v_lshl_add_u64 v[100:101], v[176:177], 0, s[8:9]
	v_lshl_add_u64 v[108:109], v[178:179], 0, s[8:9]
	global_load_dwordx4 v[96:99], v[100:101], off
	s_nop 0
	global_load_dwordx4 v[100:103], v[100:101], off offset:64
	s_nop 0
	global_load_dwordx4 v[104:107], v[108:109], off offset:16
	s_nop 0
	global_load_dwordx4 v[108:111], v[108:109], off
.LBB0_922:
	v_cvt_pk_bf16_f32 v160, v160, v161
	v_cvt_pk_bf16_f32 v161, v162, v163
	v_cvt_pk_bf16_f32 v162, v164, v165
	v_cvt_pk_bf16_f32 v164, v168, v169
	v_add_co_u32_e32 v168, vcc, s29, v190
	v_cvt_pk_bf16_f32 v163, v166, v167
	v_cvt_pk_bf16_f32 v165, v170, v171
	v_cvt_pk_bf16_f32 v166, v172, v173
	v_cvt_pk_bf16_f32 v167, v174, v175
	v_addc_co_u32_e32 v169, vcc, 0, v191, vcc
	ds_write_b64 v193, v[160:161] offset:9216
	ds_write_b64 v193, v[162:163] offset:11520
	ds_write_b64 v193, v[164:165] offset:13824
	ds_write_b64 v194, v[166:167] offset:9216
	s_nop 1
	v_permlane32_swap_b32_e32 v160, v164
	v_permlane32_swap_b32_e32 v161, v165
	v_permlane32_swap_b32_e32 v162, v166
	v_permlane32_swap_b32_e32 v163, v167
	global_store_dwordx4 v[168:169], v[160:163], off
	global_store_dwordx4 v[168:169], v[164:167], off offset:1024
	s_waitcnt lgkmcnt(0)
	s_barrier
	ds_read_b128 v[164:167], v195 offset:9216
	ds_read_b128 v[168:171], v195 offset:9280
	s_waitcnt vmcnt(20)
	v_lshlrev_b32_e32 v160, 16, v124
	v_and_b32_e32 v161, 0xffff0000, v124
	v_lshlrev_b32_e32 v162, 16, v125
	v_and_b32_e32 v163, 0xffff0000, v125
	ds_read_b128 v[172:175], v195 offset:11584
	ds_read_b128 v[198:201], v195 offset:13888
	s_waitcnt lgkmcnt(3)
	v_mfma_f32_16x16x32_bf16 v[160:163], v[112:115], v[164:167], v[160:163]
	ds_read_b128 v[202:205], v196 offset:9280
	s_cmpk_gt_u32 s34, 0x6e
	s_waitcnt lgkmcnt(3)
	v_mfma_f32_16x16x32_bf16 v[164:167], v[116:119], v[168:171], v[160:163]
	ds_read_b128 v[168:171], v195 offset:11520
	s_nop 2
	v_lshlrev_b32_e32 v160, 16, v126
	v_and_b32_e32 v161, 0xffff0000, v126
	v_lshlrev_b32_e32 v162, 16, v127
	v_and_b32_e32 v163, 0xffff0000, v127
	s_waitcnt lgkmcnt(0)
	s_nop 0
	v_mfma_f32_16x16x32_bf16 v[160:163], v[112:115], v[168:171], v[160:163]
	v_mfma_f32_16x16x32_bf16 v[168:171], v[116:119], v[172:175], v[160:163]
	ds_read_b128 v[172:175], v195 offset:13824
	s_nop 5
	v_lshlrev_b32_e32 v160, 16, v120
	v_and_b32_e32 v161, 0xffff0000, v120
	v_lshlrev_b32_e32 v162, 16, v121
	v_and_b32_e32 v163, 0xffff0000, v121
	s_waitcnt lgkmcnt(0)
	s_nop 0
	v_mfma_f32_16x16x32_bf16 v[160:163], v[112:115], v[172:175], v[160:163]
	v_mfma_f32_16x16x32_bf16 v[172:175], v[116:119], v[198:201], v[160:163]
	ds_read_b128 v[198:201], v196 offset:9216
	s_nop 5
	v_lshlrev_b32_e32 v160, 16, v122
	v_and_b32_e32 v161, 0xffff0000, v122
	v_lshlrev_b32_e32 v162, 16, v123
	v_and_b32_e32 v163, 0xffff0000, v123
	s_waitcnt lgkmcnt(0)
	s_nop 0
	v_mfma_f32_16x16x32_bf16 v[160:163], v[112:115], v[198:201], v[160:163]
	v_mfma_f32_16x16x32_bf16 v[160:163], v[116:119], v[202:205], v[160:163]
	s_cbranch_scc1 .LBB0_924
	s_add_i32 s0, s4, 0xffffe000
	s_lshl_b64 s[8:9], s[0:1], 1
	v_lshl_add_u64 v[116:117], v[176:177], 0, s[8:9]
	v_lshl_add_u64 v[124:125], v[178:179], 0, s[8:9]
	global_load_dwordx4 v[112:115], v[116:117], off
	s_nop 0
	global_load_dwordx4 v[116:119], v[116:117], off offset:64
	s_nop 0
	global_load_dwordx4 v[120:123], v[124:125], off offset:16
	s_nop 0
	global_load_dwordx4 v[124:127], v[124:125], off
.LBB0_924:
	s_cmpk_gt_u32 s34, 0x77
	s_cselect_b64 s[8:9], -1, 0
	s_and_b64 vcc, exec, s[8:9]
	s_cbranch_vccnz .LBB0_927
	s_add_i32 s0, s10, s6
	s_add_i32 s0, s0, 0x10000
	v_cvt_pk_bf16_f32 v164, v164, v165
	v_cvt_pk_bf16_f32 v165, v166, v167
	v_cvt_pk_bf16_f32 v166, v168, v169
	v_cvt_pk_bf16_f32 v167, v170, v171
	v_cvt_pk_bf16_f32 v168, v172, v173
	v_cvt_pk_bf16_f32 v169, v174, v175
	v_cvt_pk_bf16_f32 v170, v160, v161
	v_cvt_pk_bf16_f32 v171, v162, v163
	v_lshl_add_u64 v[160:161], v[186:187], 0, s[0:1]
	ds_write_b64 v193, v[164:165]
	ds_write_b64 v193, v[166:167] offset:2304
	ds_write_b64 v193, v[168:169] offset:4608
	ds_write_b64 v194, v[170:171]
	s_nop 1
	v_permlane32_swap_b32_e32 v164, v168
	v_permlane32_swap_b32_e32 v165, v169
	v_permlane32_swap_b32_e32 v166, v170
	v_permlane32_swap_b32_e32 v167, v171
	global_store_dwordx4 v[160:161], v[164:167], off
	global_store_dwordx4 v[160:161], v[168:171], off offset:1024
	s_waitcnt lgkmcnt(0)
	s_barrier
	ds_read_b128 v[164:167], v195
	ds_read_b128 v[168:171], v195 offset:64
	s_waitcnt vmcnt(54)
	v_lshlrev_b32_e32 v160, 16, v140
	v_and_b32_e32 v161, 0xffff0000, v140
	v_lshlrev_b32_e32 v162, 16, v141
	v_and_b32_e32 v163, 0xffff0000, v141
	ds_read_b128 v[172:175], v195 offset:2368
	ds_read_b128 v[198:201], v195 offset:4672
	s_waitcnt lgkmcnt(3)
	v_mfma_f32_16x16x32_bf16 v[160:163], v[128:131], v[164:167], v[160:163]
	s_cmpk_gt_u32 s34, 0x6d
	ds_read_b128 v[202:205], v196 offset:64
	s_waitcnt lgkmcnt(3)
	v_mfma_f32_16x16x32_bf16 v[164:167], v[132:135], v[168:171], v[160:163]
	ds_read_b128 v[168:171], v195 offset:2304
	s_nop 2
	v_lshlrev_b32_e32 v160, 16, v142
	v_and_b32_e32 v161, 0xffff0000, v142
	v_lshlrev_b32_e32 v162, 16, v143
	v_and_b32_e32 v163, 0xffff0000, v143
	s_waitcnt lgkmcnt(0)
	s_nop 0
	v_mfma_f32_16x16x32_bf16 v[160:163], v[128:131], v[168:171], v[160:163]
	v_mfma_f32_16x16x32_bf16 v[168:171], v[132:135], v[172:175], v[160:163]
	ds_read_b128 v[172:175], v195 offset:4608
	s_nop 5
	v_lshlrev_b32_e32 v160, 16, v136
	v_and_b32_e32 v161, 0xffff0000, v136
	v_lshlrev_b32_e32 v162, 16, v137
	v_and_b32_e32 v163, 0xffff0000, v137
	s_waitcnt lgkmcnt(0)
	s_nop 0
	v_mfma_f32_16x16x32_bf16 v[160:163], v[128:131], v[172:175], v[160:163]
	v_mfma_f32_16x16x32_bf16 v[172:175], v[132:135], v[198:201], v[160:163]
	ds_read_b128 v[198:201], v196
	s_nop 5
	v_lshlrev_b32_e32 v160, 16, v138
	v_and_b32_e32 v161, 0xffff0000, v138
	v_lshlrev_b32_e32 v162, 16, v139
	v_and_b32_e32 v163, 0xffff0000, v139
	s_waitcnt lgkmcnt(0)
	s_nop 0
	v_mfma_f32_16x16x32_bf16 v[160:163], v[128:131], v[198:201], v[160:163]
	v_mfma_f32_16x16x32_bf16 v[160:163], v[132:135], v[202:205], v[160:163]
	s_cbranch_scc1 .LBB0_927
	s_add_i32 s0, s4, 0xfffff000
	s_lshl_b64 s[24:25], s[0:1], 1
	v_lshl_add_u64 v[132:133], v[176:177], 0, s[24:25]
	v_lshl_add_u64 v[140:141], v[178:179], 0, s[24:25]
	global_load_dwordx4 v[128:131], v[132:133], off
	s_nop 0
	global_load_dwordx4 v[132:135], v[132:133], off offset:64
	s_nop 0
	global_load_dwordx4 v[136:139], v[140:141], off offset:16
	s_nop 0
	global_load_dwordx4 v[140:143], v[140:141], off
.LBB0_927:
	s_cmpk_gt_u32 s34, 0x76
	s_cbranch_scc1 .LBB0_907
	s_add_i32 s0, s10, s6
	s_add_i32 s0, s0, 0x12000
	v_cvt_pk_bf16_f32 v164, v164, v165
	v_cvt_pk_bf16_f32 v165, v166, v167
	v_cvt_pk_bf16_f32 v166, v168, v169
	v_cvt_pk_bf16_f32 v167, v170, v171
	v_cvt_pk_bf16_f32 v168, v172, v173
	v_cvt_pk_bf16_f32 v169, v174, v175
	v_cvt_pk_bf16_f32 v170, v160, v161
	v_cvt_pk_bf16_f32 v171, v162, v163
	v_lshl_add_u64 v[160:161], v[186:187], 0, s[0:1]
	ds_write_b64 v193, v[164:165] offset:9216
	ds_write_b64 v193, v[166:167] offset:11520
	ds_write_b64 v193, v[168:169] offset:13824
	ds_write_b64 v194, v[170:171] offset:9216
	s_nop 1
	v_permlane32_swap_b32_e32 v164, v168
	v_permlane32_swap_b32_e32 v165, v169
	v_permlane32_swap_b32_e32 v166, v170
	v_permlane32_swap_b32_e32 v167, v171
	global_store_dwordx4 v[160:161], v[164:167], off
	global_store_dwordx4 v[160:161], v[168:171], off offset:1024
	s_waitcnt lgkmcnt(0)
	s_barrier
	ds_read_b128 v[164:167], v195 offset:9216
	ds_read_b128 v[168:171], v195 offset:9280
	s_waitcnt vmcnt(52)
	v_lshlrev_b32_e32 v160, 16, v156
	v_and_b32_e32 v161, 0xffff0000, v156
	v_lshlrev_b32_e32 v162, 16, v157
	v_and_b32_e32 v163, 0xffff0000, v157
	ds_read_b128 v[172:175], v195 offset:11584
	ds_read_b128 v[198:201], v195 offset:13888
	s_waitcnt lgkmcnt(3)
	v_mfma_f32_16x16x32_bf16 v[160:163], v[144:147], v[164:167], v[160:163]
	s_cmpk_gt_u32 s34, 0x6c
	ds_read_b128 v[202:205], v196 offset:9280
	s_waitcnt lgkmcnt(3)
	v_mfma_f32_16x16x32_bf16 v[164:167], v[148:151], v[168:171], v[160:163]
	ds_read_b128 v[168:171], v195 offset:11520
	s_nop 2
	v_lshlrev_b32_e32 v160, 16, v158
	v_and_b32_e32 v161, 0xffff0000, v158
	v_lshlrev_b32_e32 v162, 16, v159
	v_and_b32_e32 v163, 0xffff0000, v159
	s_waitcnt lgkmcnt(0)
	s_nop 0
	v_mfma_f32_16x16x32_bf16 v[160:163], v[144:147], v[168:171], v[160:163]
	v_mfma_f32_16x16x32_bf16 v[168:171], v[148:151], v[172:175], v[160:163]
	ds_read_b128 v[172:175], v195 offset:13824
	s_nop 5
	v_lshlrev_b32_e32 v160, 16, v152
	v_and_b32_e32 v161, 0xffff0000, v152
	v_lshlrev_b32_e32 v162, 16, v153
	v_and_b32_e32 v163, 0xffff0000, v153
	s_waitcnt lgkmcnt(0)
	s_nop 0
	v_mfma_f32_16x16x32_bf16 v[160:163], v[144:147], v[172:175], v[160:163]
	v_mfma_f32_16x16x32_bf16 v[172:175], v[148:151], v[198:201], v[160:163]
	ds_read_b128 v[198:201], v196 offset:9216
	s_nop 5
	v_lshlrev_b32_e32 v160, 16, v154
	v_and_b32_e32 v161, 0xffff0000, v154
	v_lshlrev_b32_e32 v162, 16, v155
	v_and_b32_e32 v163, 0xffff0000, v155
	s_waitcnt lgkmcnt(0)
	s_nop 0
	v_mfma_f32_16x16x32_bf16 v[160:163], v[144:147], v[198:201], v[160:163]
	v_mfma_f32_16x16x32_bf16 v[160:163], v[148:151], v[202:205], v[160:163]
	s_cbranch_scc1 .LBB0_907
	s_mov_b32 s5, s1
	s_lshl_b64 s[24:25], s[4:5], 1
	v_lshl_add_u64 v[148:149], v[176:177], 0, s[24:25]
	v_lshl_add_u64 v[156:157], v[178:179], 0, s[24:25]
	global_load_dwordx4 v[144:147], v[148:149], off
	s_nop 0
	global_load_dwordx4 v[148:151], v[148:149], off offset:64
	s_nop 0
	global_load_dwordx4 v[152:155], v[156:157], off offset:16
	s_nop 0
	global_load_dwordx4 v[156:159], v[156:157], off
	s_branch .LBB0_907
